# v53: v49 + final norm rows by XCD ownership (grid 256) and the last gate->final-norm boundary XCD-local too
# speedup vs baseline: 1.0054x; 1.0054x over previous
.LBB0_1090:
	s_mov_b64 s[4:5], exec
	v_readlane_b32 s99, v255, 40
	s_bitcmp1_b32 s99, 0
	s_cbranch_scc0 .Lxl_9_full
	v_readlane_b32 s99, v255, 28
	s_cmp_lg_u32 s99, 3
	s_cbranch_scc1 .Lxl_9
	s_cmp_eq_u32 s46, 0x100
	s_cbranch_scc1 .Lxl_9

.LBB0_1108:
	v_mov_b32_e32 v18, v234
	v_readlane_b32 s0, v253, 9
	s_cmp_lg_u32 s46, 0x100
	s_cbranch_scc1 .Lfnr_gen
	v_readlane_b32 s98, v254, 59
	s_and_b32 s99, s98, 7
	s_lshl_b32 s99, s99, 12
	s_lshr_b32 s98, s98, 3
	s_lshl_b32 s98, s98, 3
	s_add_i32 s0, s99, s98
.Lfnr_gen:
	v_ashrrev_i32_e32 v0, 6, v234
	s_nop 0
	v_add_u32_e32 v16, s0, v0
	s_mov_b32 s0, 0x8000
	v_cmp_gt_i32_e32 vcc, s0, v16
	s_and_saveexec_b64 s[0:1], vcc
	v_readlane_b32 s6, v253, 10
	v_readlane_b32 s7, v253, 11
	s_cbranch_execz .LBB0_1111
	v_lshlrev_b32_e32 v0, 4, v18
	v_readlane_b32 s12, v252, 4
	v_and_b32_e32 v17, 0x3f0, v0
	v_readlane_b32 s26, v252, 18
	v_readlane_b32 s27, v252, 19
	s_nop 4
	global_load_dwordx4 v[0:3], v17, s[26:27]
	global_load_dwordx4 v[4:7], v17, s[26:27] offset:1024
	global_load_dwordx4 v[8:11], v17, s[26:27] offset:2048
	global_load_dwordx4 v[12:15], v17, s[26:27] offset:3072
	v_and_b32_e32 v17, 64, v237
	v_add_u32_e32 v17, 64, v17
	v_xor_b32_e32 v19, 32, v237
	v_cmp_lt_i32_e32 vcc, v19, v17
	s_mov_b64 s[0:1], 0xc00
	s_ashr_i32 s7, s6, 31
	v_cndmask_b32_e32 v19, v237, v19, vcc
	v_lshlrev_b32_e32 v20, 2, v19
	v_xor_b32_e32 v19, 16, v237
	v_cmp_lt_i32_e32 vcc, v19, v17
	v_readlane_b32 s14, v252, 6
	v_readlane_b32 s15, v252, 7
	v_cndmask_b32_e32 v19, v237, v19, vcc
	v_lshlrev_b32_e32 v21, 2, v19
	v_xor_b32_e32 v19, 8, v237
	v_cmp_lt_i32_e32 vcc, v19, v17
	s_mov_b64 s[2:3], 0
	s_movk_i32 s4, 0x7fff
	v_cndmask_b32_e32 v19, v237, v19, vcc
	v_lshlrev_b32_e32 v22, 2, v19
	v_xor_b32_e32 v19, 4, v237
	v_cmp_lt_i32_e32 vcc, v19, v17
	v_readlane_b32 s13, v252, 5
	v_readlane_b32 s16, v252, 8
	v_cndmask_b32_e32 v19, v237, v19, vcc
	v_lshlrev_b32_e32 v23, 2, v19
	v_xor_b32_e32 v19, 2, v237
	v_cmp_lt_i32_e32 vcc, v19, v17
	v_readlane_b32 s17, v252, 9
	v_readlane_b32 s18, v252, 10
	v_cndmask_b32_e32 v19, v237, v19, vcc
	v_lshlrev_b32_e32 v24, 2, v19
	v_xor_b32_e32 v19, 1, v237
	v_cmp_lt_i32_e32 vcc, v19, v17
	v_readlane_b32 s19, v252, 11
	v_readlane_b32 s20, v252, 12
	v_cndmask_b32_e32 v17, v237, v19, vcc
	v_lshlrev_b32_e32 v25, 2, v17
	v_ashrrev_i32_e32 v17, 31, v16
	v_lshlrev_b64 v[26:27], 12, v[16:17]
	v_and_b32_e32 v17, 63, v18
	v_lshl_or_b32 v26, v17, 4, v26
	v_lshl_add_u64 v[18:19], s[8:9], 0, v[26:27]
	v_lshl_add_u64 v[18:19], v[18:19], 0, s[0:1]
	s_lshl_b64 s[0:1], s[6:7], 12
	v_mov_b32_e32 v17, 0x358637bd
	v_readlane_b32 s21, v252, 13
	v_readlane_b32 s22, v252, 14
	v_readlane_b32 s23, v252, 15
	v_readlane_b32 s24, v252, 16
	v_readlane_b32 s25, v252, 17
	s_mov_b64 s[14:15], s[26:27]
	s_cmpk_lg_i32 s6, 0x800
	s_cbranch_scc1 .LBB0_1110
	s_mov_b32 s0, 0x100000
	s_mov_b32 s1, 0
	global_load_dwordx4 v[26:29], v[18:19], off offset:-3072
	global_load_dwordx4 v[30:33], v[18:19], off offset:-2048
	global_load_dwordx4 v[34:37], v[18:19], off offset:-1024
	global_load_dwordx4 v[38:41], v[18:19], off
	v_lshl_add_u64 v[68:69], v[18:19], 0, s[0:1]
	global_load_dwordx4 v[52:55], v[68:69], off offset:-3072
	global_load_dwordx4 v[56:59], v[68:69], off offset:-2048
	global_load_dwordx4 v[60:63], v[68:69], off offset:-1024
	global_load_dwordx4 v[64:67], v[68:69], off
	s_waitcnt vmcnt(4)
	v_mul_f32_e32 v50, v27, v27
	v_mul_f32_e32 v51, v31, v31
	v_mov_b32_e32 v44, v35
	v_mov_b32_e32 v45, v39
	v_mov_b32_e32 v42, v34
	v_mov_b32_e32 v43, v38
	v_fmac_f32_e32 v50, v26, v26
	v_fmac_f32_e32 v51, v30, v30
	v_pk_mul_f32 v[44:45], v[44:45], v[44:45]
	v_mov_b32_e32 v46, v36
	v_mov_b32_e32 v47, v40
	v_fmac_f32_e32 v50, v28, v28
	v_fmac_f32_e32 v51, v32, v32
	v_pk_fma_f32 v[42:43], v[42:43], v[42:43], v[44:45]
	v_mov_b32_e32 v48, v37
	v_mov_b32_e32 v49, v41
	v_fmac_f32_e32 v50, v29, v29
	v_fmac_f32_e32 v51, v33, v33
	v_pk_fma_f32 v[42:43], v[46:47], v[46:47], v[42:43]
	v_add_f32_e32 v44, v50, v51
	v_pk_fma_f32 v[42:43], v[48:49], v[48:49], v[42:43]
	s_nop 0
	v_add_f32_e32 v42, v44, v42
	v_add_f32_e32 v42, v42, v43
	ds_bpermute_b32 v43, v20, v42
	s_waitcnt lgkmcnt(0)
	v_add_f32_e32 v42, v42, v43
	ds_bpermute_b32 v43, v21, v42
	s_waitcnt lgkmcnt(0)
	v_add_f32_e32 v42, v42, v43
	ds_bpermute_b32 v43, v22, v42
	s_waitcnt lgkmcnt(0)
	v_add_f32_e32 v42, v42, v43
	ds_bpermute_b32 v43, v23, v42
	s_waitcnt lgkmcnt(0)
	v_add_f32_e32 v42, v42, v43
	ds_bpermute_b32 v43, v24, v42
	s_waitcnt lgkmcnt(0)
	v_add_f32_e32 v42, v42, v43
	ds_bpermute_b32 v43, v25, v42
	s_waitcnt lgkmcnt(0)
	v_add_f32_e32 v42, v42, v43
	v_fmamk_f32 v42, v42, 0x3a800000, v17
	v_rsq_f32_e32 v42, v42
	s_nop 0
	v_pk_mul_f32 v[26:27], v[26:27], v[42:43] op_sel_hi:[1,0]
	v_pk_mul_f32 v[28:29], v[28:29], v[42:43] op_sel_hi:[1,0]
	v_pk_mul_f32 v[30:31], v[30:31], v[42:43] op_sel_hi:[1,0]
	v_pk_mul_f32 v[32:33], v[32:33], v[42:43] op_sel_hi:[1,0]
	v_pk_mul_f32 v[34:35], v[34:35], v[42:43] op_sel_hi:[1,0]
	v_pk_mul_f32 v[36:37], v[36:37], v[42:43] op_sel_hi:[1,0]
	v_pk_mul_f32 v[38:39], v[38:39], v[42:43] op_sel_hi:[1,0]
	v_pk_mul_f32 v[40:41], v[40:41], v[42:43] op_sel_hi:[1,0]
	v_pk_mul_f32 v[28:29], v[2:3], v[28:29]
	v_pk_mul_f32 v[26:27], v[0:1], v[26:27]
	v_pk_mul_f32 v[32:33], v[6:7], v[32:33]
	v_pk_mul_f32 v[30:31], v[4:5], v[30:31]
	v_pk_mul_f32 v[36:37], v[10:11], v[36:37]
	v_pk_mul_f32 v[34:35], v[8:9], v[34:35]
	v_pk_mul_f32 v[40:41], v[14:15], v[40:41]
	v_pk_mul_f32 v[38:39], v[12:13], v[38:39]
	global_store_dwordx4 v[18:19], v[26:29], off offset:-3072
	global_store_dwordx4 v[18:19], v[30:33], off offset:-2048
	global_store_dwordx4 v[18:19], v[34:37], off offset:-1024
	global_store_dwordx4 v[18:19], v[38:41], off
	v_lshl_add_u64 v[18:19], v[68:69], 0, s[0:1]
	global_load_dwordx4 v[26:29], v[18:19], off offset:-3072
	global_load_dwordx4 v[30:33], v[18:19], off offset:-2048
	global_load_dwordx4 v[34:37], v[18:19], off offset:-1024
	global_load_dwordx4 v[38:41], v[18:19], off
	s_waitcnt vmcnt(8)
	v_mul_f32_e32 v50, v53, v53
	v_mul_f32_e32 v51, v57, v57
	v_mov_b32_e32 v44, v61
	v_mov_b32_e32 v45, v65
	v_mov_b32_e32 v42, v60
	v_mov_b32_e32 v43, v64
	v_fmac_f32_e32 v50, v52, v52
	v_fmac_f32_e32 v51, v56, v56
	v_pk_mul_f32 v[44:45], v[44:45], v[44:45]
	v_mov_b32_e32 v46, v62
	v_mov_b32_e32 v47, v66
	v_fmac_f32_e32 v50, v54, v54
	v_fmac_f32_e32 v51, v58, v58
	v_pk_fma_f32 v[42:43], v[42:43], v[42:43], v[44:45]
	v_mov_b32_e32 v48, v63
	v_mov_b32_e32 v49, v67
	v_fmac_f32_e32 v50, v55, v55
	v_fmac_f32_e32 v51, v59, v59
	v_pk_fma_f32 v[42:43], v[46:47], v[46:47], v[42:43]
	v_add_f32_e32 v44, v50, v51
	v_pk_fma_f32 v[42:43], v[48:49], v[48:49], v[42:43]
	s_nop 0
	v_add_f32_e32 v42, v44, v42
	v_add_f32_e32 v42, v42, v43
	ds_bpermute_b32 v43, v20, v42
	s_waitcnt lgkmcnt(0)
	v_add_f32_e32 v42, v42, v43
	ds_bpermute_b32 v43, v21, v42
	s_waitcnt lgkmcnt(0)
	v_add_f32_e32 v42, v42, v43
	ds_bpermute_b32 v43, v22, v42
	s_waitcnt lgkmcnt(0)
	v_add_f32_e32 v42, v42, v43
	ds_bpermute_b32 v43, v23, v42
	s_waitcnt lgkmcnt(0)
	v_add_f32_e32 v42, v42, v43
	ds_bpermute_b32 v43, v24, v42
	s_waitcnt lgkmcnt(0)
	v_add_f32_e32 v42, v42, v43
	ds_bpermute_b32 v43, v25, v42
	s_waitcnt lgkmcnt(0)
	v_add_f32_e32 v42, v42, v43
	v_fmamk_f32 v42, v42, 0x3a800000, v17
	v_rsq_f32_e32 v42, v42
	s_nop 0
	v_pk_mul_f32 v[52:53], v[52:53], v[42:43] op_sel_hi:[1,0]
	v_pk_mul_f32 v[54:55], v[54:55], v[42:43] op_sel_hi:[1,0]
	v_pk_mul_f32 v[56:57], v[56:57], v[42:43] op_sel_hi:[1,0]
	v_pk_mul_f32 v[58:59], v[58:59], v[42:43] op_sel_hi:[1,0]
	v_pk_mul_f32 v[60:61], v[60:61], v[42:43] op_sel_hi:[1,0]
	v_pk_mul_f32 v[62:63], v[62:63], v[42:43] op_sel_hi:[1,0]
	v_pk_mul_f32 v[64:65], v[64:65], v[42:43] op_sel_hi:[1,0]
	v_pk_mul_f32 v[66:67], v[66:67], v[42:43] op_sel_hi:[1,0]
	v_pk_mul_f32 v[54:55], v[2:3], v[54:55]
	v_pk_mul_f32 v[52:53], v[0:1], v[52:53]
	v_pk_mul_f32 v[58:59], v[6:7], v[58:59]
	v_pk_mul_f32 v[56:57], v[4:5], v[56:57]
	v_pk_mul_f32 v[62:63], v[10:11], v[62:63]
	v_pk_mul_f32 v[60:61], v[8:9], v[60:61]
	v_pk_mul_f32 v[66:67], v[14:15], v[66:67]
	v_pk_mul_f32 v[64:65], v[12:13], v[64:65]
	global_store_dwordx4 v[68:69], v[52:55], off offset:-3072
	global_store_dwordx4 v[68:69], v[56:59], off offset:-2048
	global_store_dwordx4 v[68:69], v[60:63], off offset:-1024
	global_store_dwordx4 v[68:69], v[64:67], off
	v_lshl_add_u64 v[68:69], v[18:19], 0, s[0:1]
	global_load_dwordx4 v[52:55], v[68:69], off offset:-3072
	global_load_dwordx4 v[56:59], v[68:69], off offset:-2048
	global_load_dwordx4 v[60:63], v[68:69], off offset:-1024
	global_load_dwordx4 v[64:67], v[68:69], off
	s_waitcnt vmcnt(8)
	v_mul_f32_e32 v50, v27, v27
	v_mul_f32_e32 v51, v31, v31
	v_mov_b32_e32 v44, v35
	v_mov_b32_e32 v45, v39
	v_mov_b32_e32 v42, v34
	v_mov_b32_e32 v43, v38
	v_fmac_f32_e32 v50, v26, v26
	v_fmac_f32_e32 v51, v30, v30
	v_pk_mul_f32 v[44:45], v[44:45], v[44:45]
	v_mov_b32_e32 v46, v36
	v_mov_b32_e32 v47, v40
	v_fmac_f32_e32 v50, v28, v28
	v_fmac_f32_e32 v51, v32, v32
	v_pk_fma_f32 v[42:43], v[42:43], v[42:43], v[44:45]
	v_mov_b32_e32 v48, v37
	v_mov_b32_e32 v49, v41
	v_fmac_f32_e32 v50, v29, v29
	v_fmac_f32_e32 v51, v33, v33
	v_pk_fma_f32 v[42:43], v[46:47], v[46:47], v[42:43]
	v_add_f32_e32 v44, v50, v51
	v_pk_fma_f32 v[42:43], v[48:49], v[48:49], v[42:43]
	s_nop 0
	v_add_f32_e32 v42, v44, v42
	v_add_f32_e32 v42, v42, v43
	ds_bpermute_b32 v43, v20, v42
	s_waitcnt lgkmcnt(0)
	v_add_f32_e32 v42, v42, v43
	ds_bpermute_b32 v43, v21, v42
	s_waitcnt lgkmcnt(0)
	v_add_f32_e32 v42, v42, v43
	ds_bpermute_b32 v43, v22, v42
	s_waitcnt lgkmcnt(0)
	v_add_f32_e32 v42, v42, v43
	ds_bpermute_b32 v43, v23, v42
	s_waitcnt lgkmcnt(0)
	v_add_f32_e32 v42, v42, v43
	ds_bpermute_b32 v43, v24, v42
	s_waitcnt lgkmcnt(0)
	v_add_f32_e32 v42, v42, v43
	ds_bpermute_b32 v43, v25, v42
	s_waitcnt lgkmcnt(0)
	v_add_f32_e32 v42, v42, v43
	v_fmamk_f32 v42, v42, 0x3a800000, v17
	v_rsq_f32_e32 v42, v42
	s_nop 0
	v_pk_mul_f32 v[26:27], v[26:27], v[42:43] op_sel_hi:[1,0]
	v_pk_mul_f32 v[28:29], v[28:29], v[42:43] op_sel_hi:[1,0]
	v_pk_mul_f32 v[30:31], v[30:31], v[42:43] op_sel_hi:[1,0]
	v_pk_mul_f32 v[32:33], v[32:33], v[42:43] op_sel_hi:[1,0]
	v_pk_mul_f32 v[34:35], v[34:35], v[42:43] op_sel_hi:[1,0]
	v_pk_mul_f32 v[36:37], v[36:37], v[42:43] op_sel_hi:[1,0]
	v_pk_mul_f32 v[38:39], v[38:39], v[42:43] op_sel_hi:[1,0]
	v_pk_mul_f32 v[40:41], v[40:41], v[42:43] op_sel_hi:[1,0]
	v_pk_mul_f32 v[28:29], v[2:3], v[28:29]
	v_pk_mul_f32 v[26:27], v[0:1], v[26:27]
	v_pk_mul_f32 v[32:33], v[6:7], v[32:33]
	v_pk_mul_f32 v[30:31], v[4:5], v[30:31]
	v_pk_mul_f32 v[36:37], v[10:11], v[36:37]
	v_pk_mul_f32 v[34:35], v[8:9], v[34:35]
	v_pk_mul_f32 v[40:41], v[14:15], v[40:41]
	v_pk_mul_f32 v[38:39], v[12:13], v[38:39]
	global_store_dwordx4 v[18:19], v[26:29], off offset:-3072
	global_store_dwordx4 v[18:19], v[30:33], off offset:-2048
	global_store_dwordx4 v[18:19], v[34:37], off offset:-1024
	global_store_dwordx4 v[18:19], v[38:41], off
	v_lshl_add_u64 v[18:19], v[68:69], 0, s[0:1]
	global_load_dwordx4 v[26:29], v[18:19], off offset:-3072
	global_load_dwordx4 v[30:33], v[18:19], off offset:-2048
	global_load_dwordx4 v[34:37], v[18:19], off offset:-1024
	global_load_dwordx4 v[38:41], v[18:19], off
	s_waitcnt vmcnt(8)
	v_mul_f32_e32 v50, v53, v53
	v_mul_f32_e32 v51, v57, v57
	v_mov_b32_e32 v44, v61
	v_mov_b32_e32 v45, v65
	v_mov_b32_e32 v42, v60
	v_mov_b32_e32 v43, v64
	v_fmac_f32_e32 v50, v52, v52
	v_fmac_f32_e32 v51, v56, v56
	v_pk_mul_f32 v[44:45], v[44:45], v[44:45]
	v_mov_b32_e32 v46, v62
	v_mov_b32_e32 v47, v66
	v_fmac_f32_e32 v50, v54, v54
	v_fmac_f32_e32 v51, v58, v58
	v_pk_fma_f32 v[42:43], v[42:43], v[42:43], v[44:45]
	v_mov_b32_e32 v48, v63
	v_mov_b32_e32 v49, v67
	v_fmac_f32_e32 v50, v55, v55
	v_fmac_f32_e32 v51, v59, v59
	v_pk_fma_f32 v[42:43], v[46:47], v[46:47], v[42:43]
	v_add_f32_e32 v44, v50, v51
	v_pk_fma_f32 v[42:43], v[48:49], v[48:49], v[42:43]
	s_nop 0
	v_add_f32_e32 v42, v44, v42
	v_add_f32_e32 v42, v42, v43
	ds_bpermute_b32 v43, v20, v42
	s_waitcnt lgkmcnt(0)
	v_add_f32_e32 v42, v42, v43
	ds_bpermute_b32 v43, v21, v42
	s_waitcnt lgkmcnt(0)
	v_add_f32_e32 v42, v42, v43
	ds_bpermute_b32 v43, v22, v42
	s_waitcnt lgkmcnt(0)
	v_add_f32_e32 v42, v42, v43
	ds_bpermute_b32 v43, v23, v42
	s_waitcnt lgkmcnt(0)
	v_add_f32_e32 v42, v42, v43
	ds_bpermute_b32 v43, v24, v42
	s_waitcnt lgkmcnt(0)
	v_add_f32_e32 v42, v42, v43
	ds_bpermute_b32 v43, v25, v42
	s_waitcnt lgkmcnt(0)
	v_add_f32_e32 v42, v42, v43
	v_fmamk_f32 v42, v42, 0x3a800000, v17
	v_rsq_f32_e32 v42, v42
	s_nop 0
	v_pk_mul_f32 v[52:53], v[52:53], v[42:43] op_sel_hi:[1,0]
	v_pk_mul_f32 v[54:55], v[54:55], v[42:43] op_sel_hi:[1,0]
	v_pk_mul_f32 v[56:57], v[56:57], v[42:43] op_sel_hi:[1,0]
	v_pk_mul_f32 v[58:59], v[58:59], v[42:43] op_sel_hi:[1,0]
	v_pk_mul_f32 v[60:61], v[60:61], v[42:43] op_sel_hi:[1,0]
	v_pk_mul_f32 v[62:63], v[62:63], v[42:43] op_sel_hi:[1,0]
	v_pk_mul_f32 v[64:65], v[64:65], v[42:43] op_sel_hi:[1,0]
	v_pk_mul_f32 v[66:67], v[66:67], v[42:43] op_sel_hi:[1,0]
	v_pk_mul_f32 v[54:55], v[2:3], v[54:55]
	v_pk_mul_f32 v[52:53], v[0:1], v[52:53]
	v_pk_mul_f32 v[58:59], v[6:7], v[58:59]
	v_pk_mul_f32 v[56:57], v[4:5], v[56:57]
	v_pk_mul_f32 v[62:63], v[10:11], v[62:63]
	v_pk_mul_f32 v[60:61], v[8:9], v[60:61]
	v_pk_mul_f32 v[66:67], v[14:15], v[66:67]
	v_pk_mul_f32 v[64:65], v[12:13], v[64:65]
	global_store_dwordx4 v[68:69], v[52:55], off offset:-3072
	global_store_dwordx4 v[68:69], v[56:59], off offset:-2048
	global_store_dwordx4 v[68:69], v[60:63], off offset:-1024
	global_store_dwordx4 v[68:69], v[64:67], off
	v_lshl_add_u64 v[68:69], v[18:19], 0, s[0:1]
	global_load_dwordx4 v[52:55], v[68:69], off offset:-3072
	global_load_dwordx4 v[56:59], v[68:69], off offset:-2048
	global_load_dwordx4 v[60:63], v[68:69], off offset:-1024
	global_load_dwordx4 v[64:67], v[68:69], off
	s_waitcnt vmcnt(8)
	v_mul_f32_e32 v50, v27, v27
	v_mul_f32_e32 v51, v31, v31
	v_mov_b32_e32 v44, v35
	v_mov_b32_e32 v45, v39
	v_mov_b32_e32 v42, v34
	v_mov_b32_e32 v43, v38
	v_fmac_f32_e32 v50, v26, v26
	v_fmac_f32_e32 v51, v30, v30
	v_pk_mul_f32 v[44:45], v[44:45], v[44:45]
	v_mov_b32_e32 v46, v36
	v_mov_b32_e32 v47, v40
	v_fmac_f32_e32 v50, v28, v28
	v_fmac_f32_e32 v51, v32, v32
	v_pk_fma_f32 v[42:43], v[42:43], v[42:43], v[44:45]
	v_mov_b32_e32 v48, v37
	v_mov_b32_e32 v49, v41
	v_fmac_f32_e32 v50, v29, v29
	v_fmac_f32_e32 v51, v33, v33
	v_pk_fma_f32 v[42:43], v[46:47], v[46:47], v[42:43]
	v_add_f32_e32 v44, v50, v51
	v_pk_fma_f32 v[42:43], v[48:49], v[48:49], v[42:43]
	s_nop 0
	v_add_f32_e32 v42, v44, v42
	v_add_f32_e32 v42, v42, v43
	ds_bpermute_b32 v43, v20, v42
	s_waitcnt lgkmcnt(0)
	v_add_f32_e32 v42, v42, v43
	ds_bpermute_b32 v43, v21, v42
	s_waitcnt lgkmcnt(0)
	v_add_f32_e32 v42, v42, v43
	ds_bpermute_b32 v43, v22, v42
	s_waitcnt lgkmcnt(0)
	v_add_f32_e32 v42, v42, v43
	ds_bpermute_b32 v43, v23, v42
	s_waitcnt lgkmcnt(0)
	v_add_f32_e32 v42, v42, v43
	ds_bpermute_b32 v43, v24, v42
	s_waitcnt lgkmcnt(0)
	v_add_f32_e32 v42, v42, v43
	ds_bpermute_b32 v43, v25, v42
	s_waitcnt lgkmcnt(0)
	v_add_f32_e32 v42, v42, v43
	v_fmamk_f32 v42, v42, 0x3a800000, v17
	v_rsq_f32_e32 v42, v42
	s_nop 0
	v_pk_mul_f32 v[26:27], v[26:27], v[42:43] op_sel_hi:[1,0]
	v_pk_mul_f32 v[28:29], v[28:29], v[42:43] op_sel_hi:[1,0]
	v_pk_mul_f32 v[30:31], v[30:31], v[42:43] op_sel_hi:[1,0]
	v_pk_mul_f32 v[32:33], v[32:33], v[42:43] op_sel_hi:[1,0]
	v_pk_mul_f32 v[34:35], v[34:35], v[42:43] op_sel_hi:[1,0]
	v_pk_mul_f32 v[36:37], v[36:37], v[42:43] op_sel_hi:[1,0]
	v_pk_mul_f32 v[38:39], v[38:39], v[42:43] op_sel_hi:[1,0]
	v_pk_mul_f32 v[40:41], v[40:41], v[42:43] op_sel_hi:[1,0]
	v_pk_mul_f32 v[28:29], v[2:3], v[28:29]
	v_pk_mul_f32 v[26:27], v[0:1], v[26:27]
	v_pk_mul_f32 v[32:33], v[6:7], v[32:33]
	v_pk_mul_f32 v[30:31], v[4:5], v[30:31]
	v_pk_mul_f32 v[36:37], v[10:11], v[36:37]
	v_pk_mul_f32 v[34:35], v[8:9], v[34:35]
	v_pk_mul_f32 v[40:41], v[14:15], v[40:41]
	v_pk_mul_f32 v[38:39], v[12:13], v[38:39]
	global_store_dwordx4 v[18:19], v[26:29], off offset:-3072
	global_store_dwordx4 v[18:19], v[30:33], off offset:-2048
	global_store_dwordx4 v[18:19], v[34:37], off offset:-1024
	global_store_dwordx4 v[18:19], v[38:41], off
	v_lshl_add_u64 v[18:19], v[68:69], 0, s[0:1]
	global_load_dwordx4 v[26:29], v[18:19], off offset:-3072
	global_load_dwordx4 v[30:33], v[18:19], off offset:-2048
	global_load_dwordx4 v[34:37], v[18:19], off offset:-1024
	global_load_dwordx4 v[38:41], v[18:19], off
	s_waitcnt vmcnt(8)
	v_mul_f32_e32 v50, v53, v53
	v_mul_f32_e32 v51, v57, v57
	v_mov_b32_e32 v44, v61
	v_mov_b32_e32 v45, v65
	v_mov_b32_e32 v42, v60
	v_mov_b32_e32 v43, v64
	v_fmac_f32_e32 v50, v52, v52
	v_fmac_f32_e32 v51, v56, v56
	v_pk_mul_f32 v[44:45], v[44:45], v[44:45]
	v_mov_b32_e32 v46, v62
	v_mov_b32_e32 v47, v66
	v_fmac_f32_e32 v50, v54, v54
	v_fmac_f32_e32 v51, v58, v58
	v_pk_fma_f32 v[42:43], v[42:43], v[42:43], v[44:45]
	v_mov_b32_e32 v48, v63
	v_mov_b32_e32 v49, v67
	v_fmac_f32_e32 v50, v55, v55
	v_fmac_f32_e32 v51, v59, v59
	v_pk_fma_f32 v[42:43], v[46:47], v[46:47], v[42:43]
	v_add_f32_e32 v44, v50, v51
	v_pk_fma_f32 v[42:43], v[48:49], v[48:49], v[42:43]
	s_nop 0
	v_add_f32_e32 v42, v44, v42
	v_add_f32_e32 v42, v42, v43
	ds_bpermute_b32 v43, v20, v42
	s_waitcnt lgkmcnt(0)
	v_add_f32_e32 v42, v42, v43
	ds_bpermute_b32 v43, v21, v42
	s_waitcnt lgkmcnt(0)
	v_add_f32_e32 v42, v42, v43
	ds_bpermute_b32 v43, v22, v42
	s_waitcnt lgkmcnt(0)
	v_add_f32_e32 v42, v42, v43
	ds_bpermute_b32 v43, v23, v42
	s_waitcnt lgkmcnt(0)
	v_add_f32_e32 v42, v42, v43
	ds_bpermute_b32 v43, v24, v42
	s_waitcnt lgkmcnt(0)
	v_add_f32_e32 v42, v42, v43
	ds_bpermute_b32 v43, v25, v42
	s_waitcnt lgkmcnt(0)
	v_add_f32_e32 v42, v42, v43
	v_fmamk_f32 v42, v42, 0x3a800000, v17
	v_rsq_f32_e32 v42, v42
	s_nop 0
	v_pk_mul_f32 v[52:53], v[52:53], v[42:43] op_sel_hi:[1,0]
	v_pk_mul_f32 v[54:55], v[54:55], v[42:43] op_sel_hi:[1,0]
	v_pk_mul_f32 v[56:57], v[56:57], v[42:43] op_sel_hi:[1,0]
	v_pk_mul_f32 v[58:59], v[58:59], v[42:43] op_sel_hi:[1,0]
	v_pk_mul_f32 v[60:61], v[60:61], v[42:43] op_sel_hi:[1,0]
	v_pk_mul_f32 v[62:63], v[62:63], v[42:43] op_sel_hi:[1,0]
	v_pk_mul_f32 v[64:65], v[64:65], v[42:43] op_sel_hi:[1,0]
	v_pk_mul_f32 v[66:67], v[66:67], v[42:43] op_sel_hi:[1,0]
	v_pk_mul_f32 v[54:55], v[2:3], v[54:55]
	v_pk_mul_f32 v[52:53], v[0:1], v[52:53]
	v_pk_mul_f32 v[58:59], v[6:7], v[58:59]
	v_pk_mul_f32 v[56:57], v[4:5], v[56:57]
	v_pk_mul_f32 v[62:63], v[10:11], v[62:63]
	v_pk_mul_f32 v[60:61], v[8:9], v[60:61]
	v_pk_mul_f32 v[66:67], v[14:15], v[66:67]
	v_pk_mul_f32 v[64:65], v[12:13], v[64:65]
	global_store_dwordx4 v[68:69], v[52:55], off offset:-3072
	global_store_dwordx4 v[68:69], v[56:59], off offset:-2048
	global_store_dwordx4 v[68:69], v[60:63], off offset:-1024
	global_store_dwordx4 v[68:69], v[64:67], off
	v_lshl_add_u64 v[68:69], v[18:19], 0, s[0:1]
	global_load_dwordx4 v[52:55], v[68:69], off offset:-3072
	global_load_dwordx4 v[56:59], v[68:69], off offset:-2048
	global_load_dwordx4 v[60:63], v[68:69], off offset:-1024
	global_load_dwordx4 v[64:67], v[68:69], off
	s_waitcnt vmcnt(8)
	v_mul_f32_e32 v50, v27, v27
	v_mul_f32_e32 v51, v31, v31
	v_mov_b32_e32 v44, v35
	v_mov_b32_e32 v45, v39
	v_mov_b32_e32 v42, v34
	v_mov_b32_e32 v43, v38
	v_fmac_f32_e32 v50, v26, v26
	v_fmac_f32_e32 v51, v30, v30
	v_pk_mul_f32 v[44:45], v[44:45], v[44:45]
	v_mov_b32_e32 v46, v36
	v_mov_b32_e32 v47, v40
	v_fmac_f32_e32 v50, v28, v28
	v_fmac_f32_e32 v51, v32, v32
	v_pk_fma_f32 v[42:43], v[42:43], v[42:43], v[44:45]
	v_mov_b32_e32 v48, v37
	v_mov_b32_e32 v49, v41
	v_fmac_f32_e32 v50, v29, v29
	v_fmac_f32_e32 v51, v33, v33
	v_pk_fma_f32 v[42:43], v[46:47], v[46:47], v[42:43]
	v_add_f32_e32 v44, v50, v51
	v_pk_fma_f32 v[42:43], v[48:49], v[48:49], v[42:43]
	s_nop 0
	v_add_f32_e32 v42, v44, v42
	v_add_f32_e32 v42, v42, v43
	ds_bpermute_b32 v43, v20, v42
	s_waitcnt lgkmcnt(0)
	v_add_f32_e32 v42, v42, v43
	ds_bpermute_b32 v43, v21, v42
	s_waitcnt lgkmcnt(0)
	v_add_f32_e32 v42, v42, v43
	ds_bpermute_b32 v43, v22, v42
	s_waitcnt lgkmcnt(0)
	v_add_f32_e32 v42, v42, v43
	ds_bpermute_b32 v43, v23, v42
	s_waitcnt lgkmcnt(0)
	v_add_f32_e32 v42, v42, v43
	ds_bpermute_b32 v43, v24, v42
	s_waitcnt lgkmcnt(0)
	v_add_f32_e32 v42, v42, v43
	ds_bpermute_b32 v43, v25, v42
	s_waitcnt lgkmcnt(0)
	v_add_f32_e32 v42, v42, v43
	v_fmamk_f32 v42, v42, 0x3a800000, v17
	v_rsq_f32_e32 v42, v42
	s_nop 0
	v_pk_mul_f32 v[26:27], v[26:27], v[42:43] op_sel_hi:[1,0]
	v_pk_mul_f32 v[28:29], v[28:29], v[42:43] op_sel_hi:[1,0]
	v_pk_mul_f32 v[30:31], v[30:31], v[42:43] op_sel_hi:[1,0]
	v_pk_mul_f32 v[32:33], v[32:33], v[42:43] op_sel_hi:[1,0]
	v_pk_mul_f32 v[34:35], v[34:35], v[42:43] op_sel_hi:[1,0]
	v_pk_mul_f32 v[36:37], v[36:37], v[42:43] op_sel_hi:[1,0]
	v_pk_mul_f32 v[38:39], v[38:39], v[42:43] op_sel_hi:[1,0]
	v_pk_mul_f32 v[40:41], v[40:41], v[42:43] op_sel_hi:[1,0]
	v_pk_mul_f32 v[28:29], v[2:3], v[28:29]
	v_pk_mul_f32 v[26:27], v[0:1], v[26:27]
	v_pk_mul_f32 v[32:33], v[6:7], v[32:33]
	v_pk_mul_f32 v[30:31], v[4:5], v[30:31]
	v_pk_mul_f32 v[36:37], v[10:11], v[36:37]
	v_pk_mul_f32 v[34:35], v[8:9], v[34:35]
	v_pk_mul_f32 v[40:41], v[14:15], v[40:41]
	v_pk_mul_f32 v[38:39], v[12:13], v[38:39]
	global_store_dwordx4 v[18:19], v[26:29], off offset:-3072
	global_store_dwordx4 v[18:19], v[30:33], off offset:-2048
	global_store_dwordx4 v[18:19], v[34:37], off offset:-1024
	global_store_dwordx4 v[18:19], v[38:41], off
	v_lshl_add_u64 v[18:19], v[68:69], 0, s[0:1]
	global_load_dwordx4 v[26:29], v[18:19], off offset:-3072
	global_load_dwordx4 v[30:33], v[18:19], off offset:-2048
	global_load_dwordx4 v[34:37], v[18:19], off offset:-1024
	global_load_dwordx4 v[38:41], v[18:19], off
	s_waitcnt vmcnt(8)
	v_mul_f32_e32 v50, v53, v53
	v_mul_f32_e32 v51, v57, v57
	v_mov_b32_e32 v44, v61
	v_mov_b32_e32 v45, v65
	v_mov_b32_e32 v42, v60
	v_mov_b32_e32 v43, v64
	v_fmac_f32_e32 v50, v52, v52
	v_fmac_f32_e32 v51, v56, v56
	v_pk_mul_f32 v[44:45], v[44:45], v[44:45]
	v_mov_b32_e32 v46, v62
	v_mov_b32_e32 v47, v66
	v_fmac_f32_e32 v50, v54, v54
	v_fmac_f32_e32 v51, v58, v58
	v_pk_fma_f32 v[42:43], v[42:43], v[42:43], v[44:45]
	v_mov_b32_e32 v48, v63
	v_mov_b32_e32 v49, v67
	v_fmac_f32_e32 v50, v55, v55
	v_fmac_f32_e32 v51, v59, v59
	v_pk_fma_f32 v[42:43], v[46:47], v[46:47], v[42:43]
	v_add_f32_e32 v44, v50, v51
	v_pk_fma_f32 v[42:43], v[48:49], v[48:49], v[42:43]
	s_nop 0
	v_add_f32_e32 v42, v44, v42
	v_add_f32_e32 v42, v42, v43
	ds_bpermute_b32 v43, v20, v42
	s_waitcnt lgkmcnt(0)
	v_add_f32_e32 v42, v42, v43
	ds_bpermute_b32 v43, v21, v42
	s_waitcnt lgkmcnt(0)
	v_add_f32_e32 v42, v42, v43
	ds_bpermute_b32 v43, v22, v42
	s_waitcnt lgkmcnt(0)
	v_add_f32_e32 v42, v42, v43
	ds_bpermute_b32 v43, v23, v42
	s_waitcnt lgkmcnt(0)
	v_add_f32_e32 v42, v42, v43
	ds_bpermute_b32 v43, v24, v42
	s_waitcnt lgkmcnt(0)
	v_add_f32_e32 v42, v42, v43
	ds_bpermute_b32 v43, v25, v42
	s_waitcnt lgkmcnt(0)
	v_add_f32_e32 v42, v42, v43
	v_fmamk_f32 v42, v42, 0x3a800000, v17
	v_rsq_f32_e32 v42, v42
	s_nop 0
	v_pk_mul_f32 v[52:53], v[52:53], v[42:43] op_sel_hi:[1,0]
	v_pk_mul_f32 v[54:55], v[54:55], v[42:43] op_sel_hi:[1,0]
	v_pk_mul_f32 v[56:57], v[56:57], v[42:43] op_sel_hi:[1,0]
	v_pk_mul_f32 v[58:59], v[58:59], v[42:43] op_sel_hi:[1,0]
	v_pk_mul_f32 v[60:61], v[60:61], v[42:43] op_sel_hi:[1,0]
	v_pk_mul_f32 v[62:63], v[62:63], v[42:43] op_sel_hi:[1,0]
	v_pk_mul_f32 v[64:65], v[64:65], v[42:43] op_sel_hi:[1,0]
	v_pk_mul_f32 v[66:67], v[66:67], v[42:43] op_sel_hi:[1,0]
	v_pk_mul_f32 v[54:55], v[2:3], v[54:55]
	v_pk_mul_f32 v[52:53], v[0:1], v[52:53]
	v_pk_mul_f32 v[58:59], v[6:7], v[58:59]
	v_pk_mul_f32 v[56:57], v[4:5], v[56:57]
	v_pk_mul_f32 v[62:63], v[10:11], v[62:63]
	v_pk_mul_f32 v[60:61], v[8:9], v[60:61]
	v_pk_mul_f32 v[66:67], v[14:15], v[66:67]
	v_pk_mul_f32 v[64:65], v[12:13], v[64:65]
	global_store_dwordx4 v[68:69], v[52:55], off offset:-3072
	global_store_dwordx4 v[68:69], v[56:59], off offset:-2048
	global_store_dwordx4 v[68:69], v[60:63], off offset:-1024
	global_store_dwordx4 v[68:69], v[64:67], off
	v_lshl_add_u64 v[68:69], v[18:19], 0, s[0:1]
	global_load_dwordx4 v[52:55], v[68:69], off offset:-3072
	global_load_dwordx4 v[56:59], v[68:69], off offset:-2048
	global_load_dwordx4 v[60:63], v[68:69], off offset:-1024
	global_load_dwordx4 v[64:67], v[68:69], off
	s_waitcnt vmcnt(8)
	v_mul_f32_e32 v50, v27, v27
	v_mul_f32_e32 v51, v31, v31
	v_mov_b32_e32 v44, v35
	v_mov_b32_e32 v45, v39
	v_mov_b32_e32 v42, v34
	v_mov_b32_e32 v43, v38
	v_fmac_f32_e32 v50, v26, v26
	v_fmac_f32_e32 v51, v30, v30
	v_pk_mul_f32 v[44:45], v[44:45], v[44:45]
	v_mov_b32_e32 v46, v36
	v_mov_b32_e32 v47, v40
	v_fmac_f32_e32 v50, v28, v28
	v_fmac_f32_e32 v51, v32, v32
	v_pk_fma_f32 v[42:43], v[42:43], v[42:43], v[44:45]
	v_mov_b32_e32 v48, v37
	v_mov_b32_e32 v49, v41
	v_fmac_f32_e32 v50, v29, v29
	v_fmac_f32_e32 v51, v33, v33
	v_pk_fma_f32 v[42:43], v[46:47], v[46:47], v[42:43]
	v_add_f32_e32 v44, v50, v51
	v_pk_fma_f32 v[42:43], v[48:49], v[48:49], v[42:43]
	s_nop 0
	v_add_f32_e32 v42, v44, v42
	v_add_f32_e32 v42, v42, v43
	ds_bpermute_b32 v43, v20, v42
	s_waitcnt lgkmcnt(0)
	v_add_f32_e32 v42, v42, v43
	ds_bpermute_b32 v43, v21, v42
	s_waitcnt lgkmcnt(0)
	v_add_f32_e32 v42, v42, v43
	ds_bpermute_b32 v43, v22, v42
	s_waitcnt lgkmcnt(0)
	v_add_f32_e32 v42, v42, v43
	ds_bpermute_b32 v43, v23, v42
	s_waitcnt lgkmcnt(0)
	v_add_f32_e32 v42, v42, v43
	ds_bpermute_b32 v43, v24, v42
	s_waitcnt lgkmcnt(0)
	v_add_f32_e32 v42, v42, v43
	ds_bpermute_b32 v43, v25, v42
	s_waitcnt lgkmcnt(0)
	v_add_f32_e32 v42, v42, v43
	v_fmamk_f32 v42, v42, 0x3a800000, v17
	v_rsq_f32_e32 v42, v42
	s_nop 0
	v_pk_mul_f32 v[26:27], v[26:27], v[42:43] op_sel_hi:[1,0]
	v_pk_mul_f32 v[28:29], v[28:29], v[42:43] op_sel_hi:[1,0]
	v_pk_mul_f32 v[30:31], v[30:31], v[42:43] op_sel_hi:[1,0]
	v_pk_mul_f32 v[32:33], v[32:33], v[42:43] op_sel_hi:[1,0]
	v_pk_mul_f32 v[34:35], v[34:35], v[42:43] op_sel_hi:[1,0]
	v_pk_mul_f32 v[36:37], v[36:37], v[42:43] op_sel_hi:[1,0]
	v_pk_mul_f32 v[38:39], v[38:39], v[42:43] op_sel_hi:[1,0]
	v_pk_mul_f32 v[40:41], v[40:41], v[42:43] op_sel_hi:[1,0]
	v_pk_mul_f32 v[28:29], v[2:3], v[28:29]
	v_pk_mul_f32 v[26:27], v[0:1], v[26:27]
	v_pk_mul_f32 v[32:33], v[6:7], v[32:33]
	v_pk_mul_f32 v[30:31], v[4:5], v[30:31]
	v_pk_mul_f32 v[36:37], v[10:11], v[36:37]
	v_pk_mul_f32 v[34:35], v[8:9], v[34:35]
	v_pk_mul_f32 v[40:41], v[14:15], v[40:41]
	v_pk_mul_f32 v[38:39], v[12:13], v[38:39]
	global_store_dwordx4 v[18:19], v[26:29], off offset:-3072
	global_store_dwordx4 v[18:19], v[30:33], off offset:-2048
	global_store_dwordx4 v[18:19], v[34:37], off offset:-1024
	global_store_dwordx4 v[18:19], v[38:41], off
	v_lshl_add_u64 v[18:19], v[68:69], 0, s[0:1]
	global_load_dwordx4 v[26:29], v[18:19], off offset:-3072
	global_load_dwordx4 v[30:33], v[18:19], off offset:-2048
	global_load_dwordx4 v[34:37], v[18:19], off offset:-1024
	global_load_dwordx4 v[38:41], v[18:19], off
	s_waitcnt vmcnt(8)
	v_mul_f32_e32 v50, v53, v53
	v_mul_f32_e32 v51, v57, v57
	v_mov_b32_e32 v44, v61
	v_mov_b32_e32 v45, v65
	v_mov_b32_e32 v42, v60
	v_mov_b32_e32 v43, v64
	v_fmac_f32_e32 v50, v52, v52
	v_fmac_f32_e32 v51, v56, v56
	v_pk_mul_f32 v[44:45], v[44:45], v[44:45]
	v_mov_b32_e32 v46, v62
	v_mov_b32_e32 v47, v66
	v_fmac_f32_e32 v50, v54, v54
	v_fmac_f32_e32 v51, v58, v58
	v_pk_fma_f32 v[42:43], v[42:43], v[42:43], v[44:45]
	v_mov_b32_e32 v48, v63
	v_mov_b32_e32 v49, v67
	v_fmac_f32_e32 v50, v55, v55
	v_fmac_f32_e32 v51, v59, v59
	v_pk_fma_f32 v[42:43], v[46:47], v[46:47], v[42:43]
	v_add_f32_e32 v44, v50, v51
	v_pk_fma_f32 v[42:43], v[48:49], v[48:49], v[42:43]
	s_nop 0
	v_add_f32_e32 v42, v44, v42
	v_add_f32_e32 v42, v42, v43
	ds_bpermute_b32 v43, v20, v42
	s_waitcnt lgkmcnt(0)
	v_add_f32_e32 v42, v42, v43
	ds_bpermute_b32 v43, v21, v42
	s_waitcnt lgkmcnt(0)
	v_add_f32_e32 v42, v42, v43
	ds_bpermute_b32 v43, v22, v42
	s_waitcnt lgkmcnt(0)
	v_add_f32_e32 v42, v42, v43
	ds_bpermute_b32 v43, v23, v42
	s_waitcnt lgkmcnt(0)
	v_add_f32_e32 v42, v42, v43
	ds_bpermute_b32 v43, v24, v42
	s_waitcnt lgkmcnt(0)
	v_add_f32_e32 v42, v42, v43
	ds_bpermute_b32 v43, v25, v42
	s_waitcnt lgkmcnt(0)
	v_add_f32_e32 v42, v42, v43
	v_fmamk_f32 v42, v42, 0x3a800000, v17
	v_rsq_f32_e32 v42, v42
	s_nop 0
	v_pk_mul_f32 v[52:53], v[52:53], v[42:43] op_sel_hi:[1,0]
	v_pk_mul_f32 v[54:55], v[54:55], v[42:43] op_sel_hi:[1,0]
	v_pk_mul_f32 v[56:57], v[56:57], v[42:43] op_sel_hi:[1,0]
	v_pk_mul_f32 v[58:59], v[58:59], v[42:43] op_sel_hi:[1,0]
	v_pk_mul_f32 v[60:61], v[60:61], v[42:43] op_sel_hi:[1,0]
	v_pk_mul_f32 v[62:63], v[62:63], v[42:43] op_sel_hi:[1,0]
	v_pk_mul_f32 v[64:65], v[64:65], v[42:43] op_sel_hi:[1,0]
	v_pk_mul_f32 v[66:67], v[66:67], v[42:43] op_sel_hi:[1,0]
	v_pk_mul_f32 v[54:55], v[2:3], v[54:55]
	v_pk_mul_f32 v[52:53], v[0:1], v[52:53]
	v_pk_mul_f32 v[58:59], v[6:7], v[58:59]
	v_pk_mul_f32 v[56:57], v[4:5], v[56:57]
	v_pk_mul_f32 v[62:63], v[10:11], v[62:63]
	v_pk_mul_f32 v[60:61], v[8:9], v[60:61]
	v_pk_mul_f32 v[66:67], v[14:15], v[66:67]
	v_pk_mul_f32 v[64:65], v[12:13], v[64:65]
	global_store_dwordx4 v[68:69], v[52:55], off offset:-3072
	global_store_dwordx4 v[68:69], v[56:59], off offset:-2048
	global_store_dwordx4 v[68:69], v[60:63], off offset:-1024
	global_store_dwordx4 v[68:69], v[64:67], off
	v_lshl_add_u64 v[68:69], v[18:19], 0, s[0:1]
	global_load_dwordx4 v[52:55], v[68:69], off offset:-3072
	global_load_dwordx4 v[56:59], v[68:69], off offset:-2048
	global_load_dwordx4 v[60:63], v[68:69], off offset:-1024
	global_load_dwordx4 v[64:67], v[68:69], off
	s_waitcnt vmcnt(8)
	v_mul_f32_e32 v50, v27, v27
	v_mul_f32_e32 v51, v31, v31
	v_mov_b32_e32 v44, v35
	v_mov_b32_e32 v45, v39
	v_mov_b32_e32 v42, v34
	v_mov_b32_e32 v43, v38
	v_fmac_f32_e32 v50, v26, v26
	v_fmac_f32_e32 v51, v30, v30
	v_pk_mul_f32 v[44:45], v[44:45], v[44:45]
	v_mov_b32_e32 v46, v36
	v_mov_b32_e32 v47, v40
	v_fmac_f32_e32 v50, v28, v28
	v_fmac_f32_e32 v51, v32, v32
	v_pk_fma_f32 v[42:43], v[42:43], v[42:43], v[44:45]
	v_mov_b32_e32 v48, v37
	v_mov_b32_e32 v49, v41
	v_fmac_f32_e32 v50, v29, v29
	v_fmac_f32_e32 v51, v33, v33
	v_pk_fma_f32 v[42:43], v[46:47], v[46:47], v[42:43]
	v_add_f32_e32 v44, v50, v51
	v_pk_fma_f32 v[42:43], v[48:49], v[48:49], v[42:43]
	s_nop 0
	v_add_f32_e32 v42, v44, v42
	v_add_f32_e32 v42, v42, v43
	ds_bpermute_b32 v43, v20, v42
	s_waitcnt lgkmcnt(0)
	v_add_f32_e32 v42, v42, v43
	ds_bpermute_b32 v43, v21, v42
	s_waitcnt lgkmcnt(0)
	v_add_f32_e32 v42, v42, v43
	ds_bpermute_b32 v43, v22, v42
	s_waitcnt lgkmcnt(0)
	v_add_f32_e32 v42, v42, v43
	ds_bpermute_b32 v43, v23, v42
	s_waitcnt lgkmcnt(0)
	v_add_f32_e32 v42, v42, v43
	ds_bpermute_b32 v43, v24, v42
	s_waitcnt lgkmcnt(0)
	v_add_f32_e32 v42, v42, v43
	ds_bpermute_b32 v43, v25, v42
	s_waitcnt lgkmcnt(0)
	v_add_f32_e32 v42, v42, v43
	v_fmamk_f32 v42, v42, 0x3a800000, v17
	v_rsq_f32_e32 v42, v42
	s_nop 0
	v_pk_mul_f32 v[26:27], v[26:27], v[42:43] op_sel_hi:[1,0]
	v_pk_mul_f32 v[28:29], v[28:29], v[42:43] op_sel_hi:[1,0]
	v_pk_mul_f32 v[30:31], v[30:31], v[42:43] op_sel_hi:[1,0]
	v_pk_mul_f32 v[32:33], v[32:33], v[42:43] op_sel_hi:[1,0]
	v_pk_mul_f32 v[34:35], v[34:35], v[42:43] op_sel_hi:[1,0]
	v_pk_mul_f32 v[36:37], v[36:37], v[42:43] op_sel_hi:[1,0]
	v_pk_mul_f32 v[38:39], v[38:39], v[42:43] op_sel_hi:[1,0]
	v_pk_mul_f32 v[40:41], v[40:41], v[42:43] op_sel_hi:[1,0]
	v_pk_mul_f32 v[28:29], v[2:3], v[28:29]
	v_pk_mul_f32 v[26:27], v[0:1], v[26:27]
	v_pk_mul_f32 v[32:33], v[6:7], v[32:33]
	v_pk_mul_f32 v[30:31], v[4:5], v[30:31]
	v_pk_mul_f32 v[36:37], v[10:11], v[36:37]
	v_pk_mul_f32 v[34:35], v[8:9], v[34:35]
	v_pk_mul_f32 v[40:41], v[14:15], v[40:41]
	v_pk_mul_f32 v[38:39], v[12:13], v[38:39]
	global_store_dwordx4 v[18:19], v[26:29], off offset:-3072
	global_store_dwordx4 v[18:19], v[30:33], off offset:-2048
	global_store_dwordx4 v[18:19], v[34:37], off offset:-1024
	global_store_dwordx4 v[18:19], v[38:41], off
	v_lshl_add_u64 v[18:19], v[68:69], 0, s[0:1]
	global_load_dwordx4 v[26:29], v[18:19], off offset:-3072
	global_load_dwordx4 v[30:33], v[18:19], off offset:-2048
	global_load_dwordx4 v[34:37], v[18:19], off offset:-1024
	global_load_dwordx4 v[38:41], v[18:19], off
	s_waitcnt vmcnt(8)
	v_mul_f32_e32 v50, v53, v53
	v_mul_f32_e32 v51, v57, v57
	v_mov_b32_e32 v44, v61
	v_mov_b32_e32 v45, v65
	v_mov_b32_e32 v42, v60
	v_mov_b32_e32 v43, v64
	v_fmac_f32_e32 v50, v52, v52
	v_fmac_f32_e32 v51, v56, v56
	v_pk_mul_f32 v[44:45], v[44:45], v[44:45]
	v_mov_b32_e32 v46, v62
	v_mov_b32_e32 v47, v66
	v_fmac_f32_e32 v50, v54, v54
	v_fmac_f32_e32 v51, v58, v58
	v_pk_fma_f32 v[42:43], v[42:43], v[42:43], v[44:45]
	v_mov_b32_e32 v48, v63
	v_mov_b32_e32 v49, v67
	v_fmac_f32_e32 v50, v55, v55
	v_fmac_f32_e32 v51, v59, v59
	v_pk_fma_f32 v[42:43], v[46:47], v[46:47], v[42:43]
	v_add_f32_e32 v44, v50, v51
	v_pk_fma_f32 v[42:43], v[48:49], v[48:49], v[42:43]
	s_nop 0
	v_add_f32_e32 v42, v44, v42
	v_add_f32_e32 v42, v42, v43
	ds_bpermute_b32 v43, v20, v42
	s_waitcnt lgkmcnt(0)
	v_add_f32_e32 v42, v42, v43
	ds_bpermute_b32 v43, v21, v42
	s_waitcnt lgkmcnt(0)
	v_add_f32_e32 v42, v42, v43
	ds_bpermute_b32 v43, v22, v42
	s_waitcnt lgkmcnt(0)
	v_add_f32_e32 v42, v42, v43
	ds_bpermute_b32 v43, v23, v42
	s_waitcnt lgkmcnt(0)
	v_add_f32_e32 v42, v42, v43
	ds_bpermute_b32 v43, v24, v42
	s_waitcnt lgkmcnt(0)
	v_add_f32_e32 v42, v42, v43
	ds_bpermute_b32 v43, v25, v42
	s_waitcnt lgkmcnt(0)
	v_add_f32_e32 v42, v42, v43
	v_fmamk_f32 v42, v42, 0x3a800000, v17
	v_rsq_f32_e32 v42, v42
	s_nop 0
	v_pk_mul_f32 v[52:53], v[52:53], v[42:43] op_sel_hi:[1,0]
	v_pk_mul_f32 v[54:55], v[54:55], v[42:43] op_sel_hi:[1,0]
	v_pk_mul_f32 v[56:57], v[56:57], v[42:43] op_sel_hi:[1,0]
	v_pk_mul_f32 v[58:59], v[58:59], v[42:43] op_sel_hi:[1,0]
	v_pk_mul_f32 v[60:61], v[60:61], v[42:43] op_sel_hi:[1,0]
	v_pk_mul_f32 v[62:63], v[62:63], v[42:43] op_sel_hi:[1,0]
	v_pk_mul_f32 v[64:65], v[64:65], v[42:43] op_sel_hi:[1,0]
	v_pk_mul_f32 v[66:67], v[66:67], v[42:43] op_sel_hi:[1,0]
	v_pk_mul_f32 v[54:55], v[2:3], v[54:55]
	v_pk_mul_f32 v[52:53], v[0:1], v[52:53]
	v_pk_mul_f32 v[58:59], v[6:7], v[58:59]
	v_pk_mul_f32 v[56:57], v[4:5], v[56:57]
	v_pk_mul_f32 v[62:63], v[10:11], v[62:63]
	v_pk_mul_f32 v[60:61], v[8:9], v[60:61]
	v_pk_mul_f32 v[66:67], v[14:15], v[66:67]
	v_pk_mul_f32 v[64:65], v[12:13], v[64:65]
	global_store_dwordx4 v[68:69], v[52:55], off offset:-3072
	global_store_dwordx4 v[68:69], v[56:59], off offset:-2048
	global_store_dwordx4 v[68:69], v[60:63], off offset:-1024
	global_store_dwordx4 v[68:69], v[64:67], off
	v_lshl_add_u64 v[68:69], v[18:19], 0, s[0:1]
	global_load_dwordx4 v[52:55], v[68:69], off offset:-3072
	global_load_dwordx4 v[56:59], v[68:69], off offset:-2048
	global_load_dwordx4 v[60:63], v[68:69], off offset:-1024
	global_load_dwordx4 v[64:67], v[68:69], off
	s_waitcnt vmcnt(8)
	v_mul_f32_e32 v50, v27, v27
	v_mul_f32_e32 v51, v31, v31
	v_mov_b32_e32 v44, v35
	v_mov_b32_e32 v45, v39
	v_mov_b32_e32 v42, v34
	v_mov_b32_e32 v43, v38
	v_fmac_f32_e32 v50, v26, v26
	v_fmac_f32_e32 v51, v30, v30
	v_pk_mul_f32 v[44:45], v[44:45], v[44:45]
	v_mov_b32_e32 v46, v36
	v_mov_b32_e32 v47, v40
	v_fmac_f32_e32 v50, v28, v28
	v_fmac_f32_e32 v51, v32, v32
	v_pk_fma_f32 v[42:43], v[42:43], v[42:43], v[44:45]
	v_mov_b32_e32 v48, v37
	v_mov_b32_e32 v49, v41
	v_fmac_f32_e32 v50, v29, v29
	v_fmac_f32_e32 v51, v33, v33
	v_pk_fma_f32 v[42:43], v[46:47], v[46:47], v[42:43]
	v_add_f32_e32 v44, v50, v51
	v_pk_fma_f32 v[42:43], v[48:49], v[48:49], v[42:43]
	s_nop 0
	v_add_f32_e32 v42, v44, v42
	v_add_f32_e32 v42, v42, v43
	ds_bpermute_b32 v43, v20, v42
	s_waitcnt lgkmcnt(0)
	v_add_f32_e32 v42, v42, v43
	ds_bpermute_b32 v43, v21, v42
	s_waitcnt lgkmcnt(0)
	v_add_f32_e32 v42, v42, v43
	ds_bpermute_b32 v43, v22, v42
	s_waitcnt lgkmcnt(0)
	v_add_f32_e32 v42, v42, v43
	ds_bpermute_b32 v43, v23, v42
	s_waitcnt lgkmcnt(0)
	v_add_f32_e32 v42, v42, v43
	ds_bpermute_b32 v43, v24, v42
	s_waitcnt lgkmcnt(0)
	v_add_f32_e32 v42, v42, v43
	ds_bpermute_b32 v43, v25, v42
	s_waitcnt lgkmcnt(0)
	v_add_f32_e32 v42, v42, v43
	v_fmamk_f32 v42, v42, 0x3a800000, v17
	v_rsq_f32_e32 v42, v42
	s_nop 0
	v_pk_mul_f32 v[26:27], v[26:27], v[42:43] op_sel_hi:[1,0]
	v_pk_mul_f32 v[28:29], v[28:29], v[42:43] op_sel_hi:[1,0]
	v_pk_mul_f32 v[30:31], v[30:31], v[42:43] op_sel_hi:[1,0]
	v_pk_mul_f32 v[32:33], v[32:33], v[42:43] op_sel_hi:[1,0]
	v_pk_mul_f32 v[34:35], v[34:35], v[42:43] op_sel_hi:[1,0]
	v_pk_mul_f32 v[36:37], v[36:37], v[42:43] op_sel_hi:[1,0]
	v_pk_mul_f32 v[38:39], v[38:39], v[42:43] op_sel_hi:[1,0]
	v_pk_mul_f32 v[40:41], v[40:41], v[42:43] op_sel_hi:[1,0]
	v_pk_mul_f32 v[28:29], v[2:3], v[28:29]
	v_pk_mul_f32 v[26:27], v[0:1], v[26:27]
	v_pk_mul_f32 v[32:33], v[6:7], v[32:33]
	v_pk_mul_f32 v[30:31], v[4:5], v[30:31]
	v_pk_mul_f32 v[36:37], v[10:11], v[36:37]
	v_pk_mul_f32 v[34:35], v[8:9], v[34:35]
	v_pk_mul_f32 v[40:41], v[14:15], v[40:41]
	v_pk_mul_f32 v[38:39], v[12:13], v[38:39]
	global_store_dwordx4 v[18:19], v[26:29], off offset:-3072
	global_store_dwordx4 v[18:19], v[30:33], off offset:-2048
	global_store_dwordx4 v[18:19], v[34:37], off offset:-1024
	global_store_dwordx4 v[18:19], v[38:41], off
	v_lshl_add_u64 v[18:19], v[68:69], 0, s[0:1]
	global_load_dwordx4 v[26:29], v[18:19], off offset:-3072
	global_load_dwordx4 v[30:33], v[18:19], off offset:-2048
	global_load_dwordx4 v[34:37], v[18:19], off offset:-1024
	global_load_dwordx4 v[38:41], v[18:19], off
	s_waitcnt vmcnt(8)
	v_mul_f32_e32 v50, v53, v53
	v_mul_f32_e32 v51, v57, v57
	v_mov_b32_e32 v44, v61
	v_mov_b32_e32 v45, v65
	v_mov_b32_e32 v42, v60
	v_mov_b32_e32 v43, v64
	v_fmac_f32_e32 v50, v52, v52
	v_fmac_f32_e32 v51, v56, v56
	v_pk_mul_f32 v[44:45], v[44:45], v[44:45]
	v_mov_b32_e32 v46, v62
	v_mov_b32_e32 v47, v66
	v_fmac_f32_e32 v50, v54, v54
	v_fmac_f32_e32 v51, v58, v58
	v_pk_fma_f32 v[42:43], v[42:43], v[42:43], v[44:45]
	v_mov_b32_e32 v48, v63
	v_mov_b32_e32 v49, v67
	v_fmac_f32_e32 v50, v55, v55
	v_fmac_f32_e32 v51, v59, v59
	v_pk_fma_f32 v[42:43], v[46:47], v[46:47], v[42:43]
	v_add_f32_e32 v44, v50, v51
	v_pk_fma_f32 v[42:43], v[48:49], v[48:49], v[42:43]
	s_nop 0
	v_add_f32_e32 v42, v44, v42
	v_add_f32_e32 v42, v42, v43
	ds_bpermute_b32 v43, v20, v42
	s_waitcnt lgkmcnt(0)
	v_add_f32_e32 v42, v42, v43
	ds_bpermute_b32 v43, v21, v42
	s_waitcnt lgkmcnt(0)
	v_add_f32_e32 v42, v42, v43
	ds_bpermute_b32 v43, v22, v42
	s_waitcnt lgkmcnt(0)
	v_add_f32_e32 v42, v42, v43
	ds_bpermute_b32 v43, v23, v42
	s_waitcnt lgkmcnt(0)
	v_add_f32_e32 v42, v42, v43
	ds_bpermute_b32 v43, v24, v42
	s_waitcnt lgkmcnt(0)
	v_add_f32_e32 v42, v42, v43
	ds_bpermute_b32 v43, v25, v42
	s_waitcnt lgkmcnt(0)
	v_add_f32_e32 v42, v42, v43
	v_fmamk_f32 v42, v42, 0x3a800000, v17
	v_rsq_f32_e32 v42, v42
	s_nop 0
	v_pk_mul_f32 v[52:53], v[52:53], v[42:43] op_sel_hi:[1,0]
	v_pk_mul_f32 v[54:55], v[54:55], v[42:43] op_sel_hi:[1,0]
	v_pk_mul_f32 v[56:57], v[56:57], v[42:43] op_sel_hi:[1,0]
	v_pk_mul_f32 v[58:59], v[58:59], v[42:43] op_sel_hi:[1,0]
	v_pk_mul_f32 v[60:61], v[60:61], v[42:43] op_sel_hi:[1,0]
	v_pk_mul_f32 v[62:63], v[62:63], v[42:43] op_sel_hi:[1,0]
	v_pk_mul_f32 v[64:65], v[64:65], v[42:43] op_sel_hi:[1,0]
	v_pk_mul_f32 v[66:67], v[66:67], v[42:43] op_sel_hi:[1,0]
	v_pk_mul_f32 v[54:55], v[2:3], v[54:55]
	v_pk_mul_f32 v[52:53], v[0:1], v[52:53]
	v_pk_mul_f32 v[58:59], v[6:7], v[58:59]
	v_pk_mul_f32 v[56:57], v[4:5], v[56:57]
	v_pk_mul_f32 v[62:63], v[10:11], v[62:63]
	v_pk_mul_f32 v[60:61], v[8:9], v[60:61]
	v_pk_mul_f32 v[66:67], v[14:15], v[66:67]
	v_pk_mul_f32 v[64:65], v[12:13], v[64:65]
	global_store_dwordx4 v[68:69], v[52:55], off offset:-3072
	global_store_dwordx4 v[68:69], v[56:59], off offset:-2048
	global_store_dwordx4 v[68:69], v[60:63], off offset:-1024
	global_store_dwordx4 v[68:69], v[64:67], off
	v_lshl_add_u64 v[68:69], v[18:19], 0, s[0:1]
	global_load_dwordx4 v[52:55], v[68:69], off offset:-3072
	global_load_dwordx4 v[56:59], v[68:69], off offset:-2048
	global_load_dwordx4 v[60:63], v[68:69], off offset:-1024
	global_load_dwordx4 v[64:67], v[68:69], off
	s_waitcnt vmcnt(8)
	v_mul_f32_e32 v50, v27, v27
	v_mul_f32_e32 v51, v31, v31
	v_mov_b32_e32 v44, v35
	v_mov_b32_e32 v45, v39
	v_mov_b32_e32 v42, v34
	v_mov_b32_e32 v43, v38
	v_fmac_f32_e32 v50, v26, v26
	v_fmac_f32_e32 v51, v30, v30
	v_pk_mul_f32 v[44:45], v[44:45], v[44:45]
	v_mov_b32_e32 v46, v36
	v_mov_b32_e32 v47, v40
	v_fmac_f32_e32 v50, v28, v28
	v_fmac_f32_e32 v51, v32, v32
	v_pk_fma_f32 v[42:43], v[42:43], v[42:43], v[44:45]
	v_mov_b32_e32 v48, v37
	v_mov_b32_e32 v49, v41
	v_fmac_f32_e32 v50, v29, v29
	v_fmac_f32_e32 v51, v33, v33
	v_pk_fma_f32 v[42:43], v[46:47], v[46:47], v[42:43]
	v_add_f32_e32 v44, v50, v51
	v_pk_fma_f32 v[42:43], v[48:49], v[48:49], v[42:43]
	s_nop 0
	v_add_f32_e32 v42, v44, v42
	v_add_f32_e32 v42, v42, v43
	ds_bpermute_b32 v43, v20, v42
	s_waitcnt lgkmcnt(0)
	v_add_f32_e32 v42, v42, v43
	ds_bpermute_b32 v43, v21, v42
	s_waitcnt lgkmcnt(0)
	v_add_f32_e32 v42, v42, v43
	ds_bpermute_b32 v43, v22, v42
	s_waitcnt lgkmcnt(0)
	v_add_f32_e32 v42, v42, v43
	ds_bpermute_b32 v43, v23, v42
	s_waitcnt lgkmcnt(0)
	v_add_f32_e32 v42, v42, v43
	ds_bpermute_b32 v43, v24, v42
	s_waitcnt lgkmcnt(0)
	v_add_f32_e32 v42, v42, v43
	ds_bpermute_b32 v43, v25, v42
	s_waitcnt lgkmcnt(0)
	v_add_f32_e32 v42, v42, v43
	v_fmamk_f32 v42, v42, 0x3a800000, v17
	v_rsq_f32_e32 v42, v42
	s_nop 0
	v_pk_mul_f32 v[26:27], v[26:27], v[42:43] op_sel_hi:[1,0]
	v_pk_mul_f32 v[28:29], v[28:29], v[42:43] op_sel_hi:[1,0]
	v_pk_mul_f32 v[30:31], v[30:31], v[42:43] op_sel_hi:[1,0]
	v_pk_mul_f32 v[32:33], v[32:33], v[42:43] op_sel_hi:[1,0]
	v_pk_mul_f32 v[34:35], v[34:35], v[42:43] op_sel_hi:[1,0]
	v_pk_mul_f32 v[36:37], v[36:37], v[42:43] op_sel_hi:[1,0]
	v_pk_mul_f32 v[38:39], v[38:39], v[42:43] op_sel_hi:[1,0]
	v_pk_mul_f32 v[40:41], v[40:41], v[42:43] op_sel_hi:[1,0]
	v_pk_mul_f32 v[28:29], v[2:3], v[28:29]
	v_pk_mul_f32 v[26:27], v[0:1], v[26:27]
	v_pk_mul_f32 v[32:33], v[6:7], v[32:33]
	v_pk_mul_f32 v[30:31], v[4:5], v[30:31]
	v_pk_mul_f32 v[36:37], v[10:11], v[36:37]
	v_pk_mul_f32 v[34:35], v[8:9], v[34:35]
	v_pk_mul_f32 v[40:41], v[14:15], v[40:41]
	v_pk_mul_f32 v[38:39], v[12:13], v[38:39]
	global_store_dwordx4 v[18:19], v[26:29], off offset:-3072
	global_store_dwordx4 v[18:19], v[30:33], off offset:-2048
	global_store_dwordx4 v[18:19], v[34:37], off offset:-1024
	global_store_dwordx4 v[18:19], v[38:41], off
	s_waitcnt vmcnt(4)
	v_mul_f32_e32 v50, v53, v53
	v_mul_f32_e32 v51, v57, v57
	v_mov_b32_e32 v44, v61
	v_mov_b32_e32 v45, v65
	v_mov_b32_e32 v42, v60
	v_mov_b32_e32 v43, v64
	v_fmac_f32_e32 v50, v52, v52
	v_fmac_f32_e32 v51, v56, v56
	v_pk_mul_f32 v[44:45], v[44:45], v[44:45]
	v_mov_b32_e32 v46, v62
	v_mov_b32_e32 v47, v66
	v_fmac_f32_e32 v50, v54, v54
	v_fmac_f32_e32 v51, v58, v58
	v_pk_fma_f32 v[42:43], v[42:43], v[42:43], v[44:45]
	v_mov_b32_e32 v48, v63
	v_mov_b32_e32 v49, v67
	v_fmac_f32_e32 v50, v55, v55
	v_fmac_f32_e32 v51, v59, v59
	v_pk_fma_f32 v[42:43], v[46:47], v[46:47], v[42:43]
	v_add_f32_e32 v44, v50, v51
	v_pk_fma_f32 v[42:43], v[48:49], v[48:49], v[42:43]
	s_nop 0
	v_add_f32_e32 v42, v44, v42
	v_add_f32_e32 v42, v42, v43
	ds_bpermute_b32 v43, v20, v42
	s_waitcnt lgkmcnt(0)
	v_add_f32_e32 v42, v42, v43
	ds_bpermute_b32 v43, v21, v42
	s_waitcnt lgkmcnt(0)
	v_add_f32_e32 v42, v42, v43
	ds_bpermute_b32 v43, v22, v42
	s_waitcnt lgkmcnt(0)
	v_add_f32_e32 v42, v42, v43
	ds_bpermute_b32 v43, v23, v42
	s_waitcnt lgkmcnt(0)
	v_add_f32_e32 v42, v42, v43
	ds_bpermute_b32 v43, v24, v42
	s_waitcnt lgkmcnt(0)
	v_add_f32_e32 v42, v42, v43
	ds_bpermute_b32 v43, v25, v42
	s_waitcnt lgkmcnt(0)
	v_add_f32_e32 v42, v42, v43
	v_fmamk_f32 v42, v42, 0x3a800000, v17
	v_rsq_f32_e32 v42, v42
	s_nop 0
	v_pk_mul_f32 v[52:53], v[52:53], v[42:43] op_sel_hi:[1,0]
	v_pk_mul_f32 v[54:55], v[54:55], v[42:43] op_sel_hi:[1,0]
	v_pk_mul_f32 v[56:57], v[56:57], v[42:43] op_sel_hi:[1,0]
	v_pk_mul_f32 v[58:59], v[58:59], v[42:43] op_sel_hi:[1,0]
	v_pk_mul_f32 v[60:61], v[60:61], v[42:43] op_sel_hi:[1,0]
	v_pk_mul_f32 v[62:63], v[62:63], v[42:43] op_sel_hi:[1,0]
	v_pk_mul_f32 v[64:65], v[64:65], v[42:43] op_sel_hi:[1,0]
	v_pk_mul_f32 v[66:67], v[66:67], v[42:43] op_sel_hi:[1,0]
	v_pk_mul_f32 v[54:55], v[2:3], v[54:55]
	v_pk_mul_f32 v[52:53], v[0:1], v[52:53]
	v_pk_mul_f32 v[58:59], v[6:7], v[58:59]
	v_pk_mul_f32 v[56:57], v[4:5], v[56:57]
	v_pk_mul_f32 v[62:63], v[10:11], v[62:63]
	v_pk_mul_f32 v[60:61], v[8:9], v[60:61]
	v_pk_mul_f32 v[66:67], v[14:15], v[66:67]
	v_pk_mul_f32 v[64:65], v[12:13], v[64:65]
	global_store_dwordx4 v[68:69], v[52:55], off offset:-3072
	global_store_dwordx4 v[68:69], v[56:59], off offset:-2048
	global_store_dwordx4 v[68:69], v[60:63], off offset:-1024
	global_store_dwordx4 v[68:69], v[64:67], off
	s_branch .LBB0_1111
